# RW scan consumer setprio 2; DN chunk2 loop: batched ds_reads + counted lgkmcnt, vmcnt(4) instead of vmcnt(0)
# baseline (speedup 1.0000x reference)
.LBB0_168:
	s_and_saveexec_b64 s[44:45], s[8:9]
	s_xor_b64 s[44:45], exec, s[44:45]
	s_cbranch_execz .LBB0_175
	s_setprio 2
	s_cmpk_lg_i32 s29, 0xf000
	s_cselect_b64 s[46:47], -1, 0
	s_or_b64 s[46:47], s[42:43], s[46:47]
	s_and_b64 vcc, exec, s[46:47]
	s_cbranch_vccnz .LBB0_171
	ds_read_b128 v[30:33], v120
	s_waitcnt lgkmcnt(0)
	v_cvt_pk_bf16_f32 v30, v30, v31
	v_cvt_pk_bf16_f32 v31, v32, v33
	global_store_dwordx2 v[72:73], v[30:31], off

.LBB0_198:
	s_setprio 0
	s_mov_b64 s[6:7], 0

.LBB0_285:
	s_or_b64 exec, exec, s[8:9]
	s_lshl_b32 s6, s2, 5
	s_and_b32 s6, s6, 0xe0
	s_bfe_u32 s7, s2, 0x50003
	s_or_b32 s8, s6, s7
	v_readlane_b32 s6, v244, 4
	v_readlane_b32 s7, v244, 5
	s_and_b64 s[6:7], s[6:7], exec
	s_cselect_b32 s18, s8, s2
	s_ashr_i32 s10, s18, 5
	s_bfe_u32 s19, s18, 0x30002
	s_ashr_i32 s11, s10, 31
	s_lshl_b32 s6, s10, 9
	s_lshl_b32 s7, s19, 6
	s_lshl_b64 s[20:21], s[10:11], 12
	s_or_b32 s12, s7, s6
	s_ashr_i32 s13, s12, 31
	v_lshl_add_u64 v[2:3], s[20:21], 0, v[46:47]
	v_lshl_add_u64 v[6:7], s[20:21], 0, v[50:51]
	v_lshl_add_u64 v[14:15], s[20:21], 0, v[56:57]
	v_lshl_add_u64 v[18:19], s[20:21], 0, v[60:61]
	s_lshl_b64 s[8:9], s[12:13], 14
	v_mad_u64_u32 v[4:5], s[6:7], v2, s87, v[48:49]
	s_lshl_b32 s62, s19, 8
	v_mad_u64_u32 v[8:9], s[6:7], v6, s87, v[52:53]
	v_mad_u64_u32 v[16:17], s[6:7], v14, s87, v[58:59]
	v_mad_u64_u32 v[20:21], s[6:7], v18, s87, v[62:63]
	s_add_u32 s6, s16, s8
	s_addc_u32 s7, s17, s9
	s_lshl_b32 s11, s18, 5
	v_lshl_add_u64 v[26:27], s[20:21], 0, v[38:39]
	s_and_b32 s11, s11, 0x60
	v_mad_u64_u32 v[28:29], s[20:21], v26, s87, v[40:41]
	v_or_b32_e32 v30, s11, v42
	v_mad_i32_i24 v29, v27, s87, v29
	v_or_b32_e32 v32, v68, v30
	v_mad_i32_i24 v9, v7, s87, v9
	v_mad_i32_i24 v21, v19, s87, v21
	v_lshl_add_u64 v[26:27], v[28:29], 0, s[62:63]
	v_mov_b32_e32 v103, v1
	v_ashrrev_i32_e32 v33, 31, v32
	v_mov_b32_e32 v31, v1
	v_mad_i32_i24 v5, v3, s87, v5
	v_lshl_add_u64 v[6:7], v[8:9], 0, s[62:63]
	v_mov_b32_e32 v99, v1
	v_mov_b32_e32 v101, v1
	v_mad_i32_i24 v17, v15, s87, v17
	v_lshl_add_u64 v[18:19], v[20:21], 0, s[62:63]
	v_lshl_add_u64 v[26:27], v[26:27], 0, v[102:103]
	v_lshlrev_b64 v[32:33], 1, v[32:33]
	v_lshl_add_u64 v[30:31], v[68:69], 0, v[30:31]
	v_lshl_add_u64 v[22:23], v[44:45], 0, s[8:9]
	v_lshl_add_u64 v[2:3], v[4:5], 0, s[62:63]
	v_mov_b32_e32 v97, v1
	v_lshl_add_u64 v[6:7], v[6:7], 0, v[98:99]
	v_lshl_add_u64 v[14:15], v[16:17], 0, s[62:63]
	v_lshl_add_u64 v[18:19], v[18:19], 0, v[98:99]
	v_lshl_add_u64 v[26:27], v[26:27], 0, v[100:101]
	v_lshl_add_u64 v[34:35], s[6:7], 0, v[32:33]
	v_lshlrev_b64 v[30:31], 1, v[30:31]
	s_lshl_b64 s[12:13], s[12:13], 2
	v_lshl_add_u64 v[2:3], v[2:3], 0, v[96:97]
	v_lshl_add_u64 v[6:7], v[6:7], 0, v[100:101]
	v_lshl_add_u64 v[10:11], v[54:55], 1, v[22:23]
	v_lshl_add_u64 v[14:15], v[14:15], 0, v[96:97]
	v_lshl_add_u64 v[18:19], v[18:19], 0, v[100:101]
	v_lshl_add_u64 v[22:23], v[64:65], 1, v[22:23]
	global_load_dwordx4 v[26:29], v[26:27], off
	s_add_u32 s20, s14, s12
	global_load_ushort v36, v[34:35], off
	v_lshl_add_u64 v[34:35], s[6:7], 0, v[30:31]
	global_load_dwordx4 v[2:5], v[2:3], off
	s_addc_u32 s21, s15, s13
	global_load_dwordx4 v[6:9], v[6:7], off
	s_mov_b32 s19, s9
	global_load_dwordx4 v[10:13], v[10:11], off
	v_lshl_add_u64 v[124:125], v[92:93], 0, s[8:9]
	global_load_dwordx4 v[14:17], v[14:15], off
	v_lshl_add_u64 v[126:127], v[94:95], 0, s[8:9]
	global_load_dwordx4 v[18:21], v[18:19], off
	s_nop 0
	global_load_dwordx4 v[22:25], v[22:23], off
	s_nop 0
	global_load_ushort v37, v[34:35], off offset:256
	global_load_ushort v97, v[34:35], off offset:512
	s_nop 0
	global_load_ushort v34, v[34:35], off offset:768
	s_waitcnt vmcnt(2)
	v_perm_b32 v99, v37, v36, s78
	global_load_dword v106, v1, s[20:21]
	s_mul_hi_i32 s21, s10, 0x2200000
	s_mul_i32 s10, s10, 0x2200000
	s_or_b32 s20, s10, s62
	s_and_b32 s10, s18, 3
	s_lshl_b32 s10, s10, 6
	s_or_b32 s18, s8, s10
	s_add_u32 s10, s12, 0x1dc80004
	s_addc_u32 s12, s13, 0
	v_lshl_add_u64 v[112:113], s[18:19], 0, v[84:85]
	s_add_u32 s18, s8, 0x4004200
	s_addc_u32 s19, s9, 0
	v_lshl_add_u64 v[118:119], s[18:19], 0, v[30:31]
	s_add_u32 s18, s8, 0x4004000
	s_addc_u32 s19, s9, 0
	v_mov_b32_e32 v30, 0
	s_waitcnt vmcnt(1)
	v_perm_b32 v97, v34, v97, s78
	v_lshl_add_u64 v[108:109], s[20:21], 0, v[80:81]
	v_lshl_add_u64 v[110:111], s[20:21], 0, v[82:83]
	v_lshl_add_u64 v[114:115], s[20:21], 0, v[86:87]
	v_lshl_add_u64 v[116:117], s[20:21], 0, v[88:89]
	v_lshl_add_u64 v[120:121], s[20:21], 0, v[90:91]
	v_lshl_add_u64 v[122:123], s[18:19], 0, v[32:33]
	s_mov_b32 s8, 63
	v_mov_b32_e32 v31, v30
	v_mov_b32_e32 v32, v30
	v_mov_b32_e32 v33, v30
	v_mov_b32_e32 v34, v30
	v_mov_b32_e32 v35, v30
	v_mov_b32_e32 v36, v30
	v_mov_b32_e32 v37, v30
	s_waitcnt vmcnt(0)
.LBB0_286:
	v_add_u32_e32 v101, v43, v107
	s_add_u32 s18, s94, s10
	s_waitcnt lgkmcnt(0)
	s_barrier
	ds_write_b128 v76, v[2:5]
	ds_write_b128 v101, v[6:9] offset:34816
	ds_write_b128 v76, v[10:13] offset:53248
	ds_write_b128 v78, v[14:17]
	ds_write_b128 v145, v[18:21] offset:34816
	ds_write_b128 v78, v[22:25] offset:53248
	ds_write_b128 v129, v[26:29]
	v_lshl_add_u64 v[2:3], s[94:95], 0, v[108:109]
	v_lshl_add_u64 v[6:7], s[94:95], 0, v[110:111]
	v_lshl_add_u64 v[10:11], s[94:95], 0, v[126:127]
	v_lshl_add_u64 v[14:15], s[94:95], 0, v[114:115]
	v_lshl_add_u64 v[18:19], s[94:95], 0, v[116:117]
	v_lshl_add_u64 v[22:23], s[94:95], 0, v[124:125]
	v_lshl_add_u64 v[26:27], s[94:95], 0, v[120:121]
	v_lshl_add_u64 v[146:147], s[94:95], 0, v[122:123]
	v_lshl_add_u64 v[148:149], s[94:95], 0, v[118:119]
	s_addc_u32 s19, s95, s12
	s_waitcnt vmcnt(4)
	v_mov_b32_e32 v128, v106
	global_load_dwordx4 v[2:5], v[2:3], off
	v_pk_mul_f32 v[32:33], v[32:33], v[128:129] op_sel_hi:[1,0]
	global_load_dwordx4 v[6:9], v[6:7], off
	v_pk_mul_f32 v[30:31], v[30:31], v[128:129] op_sel_hi:[1,0]
	global_load_dwordx4 v[10:13], v[10:11], off
	v_pk_mul_f32 v[36:37], v[36:37], v[128:129] op_sel_hi:[1,0]
	global_load_dwordx4 v[14:17], v[14:15], off
	v_pk_mul_f32 v[34:35], v[34:35], v[128:129] op_sel_hi:[1,0]
	global_load_dwordx4 v[18:21], v[18:19], off
	s_add_u32 s10, s10, 4
	global_load_dwordx4 v[22:25], v[22:23], off
	s_addc_u32 s12, s12, 0
	global_load_dwordx4 v[26:29], v[26:27], off
	s_add_i32 s8, s8, -1
	global_load_ushort v103, v[146:147], off
	s_nop 0
	global_load_ushort v147, v[148:149], off offset:-256
	global_load_ushort v105, v[148:149], off
	global_load_ushort v146, v[148:149], off offset:256
	global_load_dword v106, v1, s[18:19]
	s_waitcnt lgkmcnt(0)
	s_barrier
	ds_read_b128 v[180:183], v130
	ds_read_b128 v[196:199], v131 offset:53248
	ds_read_b128 v[184:187], v130 offset:64
	ds_read_b128 v[200:203], v131 offset:53312
	ds_read_b128 v[188:191], v130 offset:128
	ds_read_b128 v[208:211], v131 offset:53376
	ds_read_b128 v[192:195], v130 offset:192
	ds_read_b128 v[212:215], v131 offset:53440
	ds_read_b128 v[216:219], v131
	ds_read_b128 v[220:223], v131 offset:64
	ds_read_b128 v[224:227], v131 offset:128
	ds_read_b128 v[228:231], v131 offset:192
	v_lshl_add_u64 v[108:109], v[108:109], 0, s[56:57]
	v_lshl_add_u64 v[110:111], v[110:111], 0, s[56:57]
	v_lshl_add_u64 v[114:115], v[114:115], 0, s[56:57]
	s_waitcnt lgkmcnt(10)
	v_mfma_f32_16x16x32_bf16 v[152:155], v[196:199], v[180:183], 0
	ds_read_b128 v[232:235], v133
	v_lshl_add_u64 v[116:117], v[116:117], 0, s[56:57]
	s_waitcnt lgkmcnt(9)
	v_mfma_f32_16x16x32_bf16 v[152:155], v[200:203], v[184:187], v[152:155]
	ds_read_b128 v[236:239], v133 offset:64
	v_lshl_add_u64 v[118:119], v[118:119], 0, s[4:5]
	s_waitcnt lgkmcnt(8)
	v_mfma_f32_16x16x32_bf16 v[152:155], v[208:211], v[188:191], v[152:155]
	ds_read_b128 v[240:243], v135 offset:34816
	v_lshl_add_u64 v[120:121], v[120:121], 0, s[56:57]
	s_waitcnt lgkmcnt(7)
	v_mfma_f32_16x16x32_bf16 v[152:155], v[212:215], v[192:195], v[152:155]
	ds_read_b128 v[176:179], v135 offset:34880
	v_lshl_add_u64 v[122:123], v[122:123], 0, s[4:5]
	s_waitcnt lgkmcnt(7)
	v_mfma_f32_16x16x32_bf16 v[148:151], v[216:219], v[180:183], 0
	v_lshl_add_u64 v[124:125], v[124:125], 0, s[4:5]
	s_waitcnt lgkmcnt(6)
	v_mfma_f32_16x16x32_bf16 v[148:151], v[220:223], v[184:187], v[148:151]
	v_lshl_add_u64 v[126:127], v[126:127], 0, s[4:5]
	s_waitcnt lgkmcnt(5)
	v_mfma_f32_16x16x32_bf16 v[148:151], v[224:227], v[188:191], v[148:151]
	v_and_b32_e32 v157, 0xffff0000, v99
	s_waitcnt lgkmcnt(4)
	v_mfma_f32_16x16x32_bf16 v[148:151], v[228:231], v[192:195], v[148:151]
	v_lshlrev_b32_e32 v156, 16, v99
	v_and_b32_e32 v159, 0xffff0000, v97
	v_lshlrev_b32_e32 v158, 16, v97
	v_pk_add_f32 v[152:153], v[156:157], v[152:153] neg_lo:[0,1] neg_hi:[0,1]
	v_pk_add_f32 v[154:155], v[158:159], v[154:155] neg_lo:[0,1] neg_hi:[0,1]
	v_cvt_pk_bf16_f32 v152, v152, v153
	v_cvt_pk_bf16_f32 v153, v154, v155
	ds_write_b64 v132, v[152:153]
	s_waitcnt lgkmcnt(0)
	s_barrier
	ds_read_b128 v[180:183], v134
	ds_read_b128 v[184:187], v134 offset:64
	ds_read_b128 v[188:191], v136
	ds_read_b128 v[192:195], v136 offset:64
	ds_read_b128 v[196:199], v136 offset:2304
	ds_read_b128 v[200:203], v136 offset:2368
	s_waitcnt vmcnt(3)
	v_perm_b32 v99, v147, v103, s78
	s_waitcnt lgkmcnt(5)
	v_mfma_f32_16x16x32_bf16 v[148:151], v[232:235], v[180:183], v[148:151]
	v_lshl_add_u64 v[152:153], s[94:95], 0, v[112:113]
	s_waitcnt lgkmcnt(4)
	v_mfma_f32_16x16x32_bf16 v[148:151], v[236:239], v[184:187], v[148:151]
	v_lshl_add_u64 v[112:113], v[112:113], 0, s[4:5]
	s_waitcnt lgkmcnt(3)
	v_mfma_f32_16x16x32_bf16 v[30:33], v[240:243], v[188:191], v[30:33]
	s_waitcnt lgkmcnt(2)
	v_mfma_f32_16x16x32_bf16 v[30:33], v[176:179], v[192:195], v[30:33]
	s_waitcnt lgkmcnt(1)
	v_mfma_f32_16x16x32_bf16 v[34:37], v[240:243], v[196:199], v[34:37]
	s_waitcnt lgkmcnt(0)
	v_mfma_f32_16x16x32_bf16 v[34:37], v[176:179], v[200:203], v[34:37]
	s_nop 0
	v_cvt_pk_bf16_f32 v97, v148, s0
	global_store_short v[152:153], v97, off offset:-512
	v_cvt_pk_bf16_f32 v97, v149, s0
	global_store_short v[152:153], v97, off offset:-256
	v_cvt_pk_bf16_f32 v97, v150, s0
	global_store_short v[152:153], v97, off
	v_cvt_pk_bf16_f32 v97, v151, s0
	global_store_short v[152:153], v97, off offset:256
	s_waitcnt vmcnt(5)
	v_perm_b32 v97, v146, v105, s78
	v_cvt_pk_bf16_f32 v156, v30, v31
	v_cvt_pk_bf16_f32 v157, v32, v33
	ds_write_b64 v137, v[156:157]
	v_cvt_pk_bf16_f32 v158, v34, v35
	v_cvt_pk_bf16_f32 v159, v36, v37
	ds_write_b64 v137, v[158:159] offset:4352
	s_cmp_eq_u32 s8, 0
	s_cbranch_scc0 .LBB0_286
	s_waitcnt lgkmcnt(0)
	s_barrier
	ds_write_b128 v76, v[2:5]
	ds_write_b128 v101, v[6:9] offset:34816
	ds_write_b128 v76, v[10:13] offset:53248
	ds_write_b128 v78, v[14:17]
	ds_write_b128 v145, v[18:21] offset:34816
	ds_write_b128 v78, v[22:25] offset:53248
	ds_write_b128 v129, v[26:29]
	s_waitcnt lgkmcnt(0)
	s_barrier
	ds_read_b128 v[2:5], v131 offset:53248
	ds_read_b128 v[6:9], v130
	ds_read_b128 v[10:13], v130 offset:64
	ds_read_b128 v[14:17], v131 offset:53312
	s_waitcnt lgkmcnt(2)
	v_mfma_f32_16x16x32_bf16 v[2:5], v[2:5], v[6:9], 0
	ds_read_b128 v[18:21], v131
	ds_read_b128 v[22:25], v131 offset:64
	v_lshlrev_b32_e32 v27, 16, v147
	v_lshlrev_b32_e32 v26, 16, v103
	s_waitcnt lgkmcnt(2)
	v_mfma_f32_16x16x32_bf16 v[2:5], v[14:17], v[10:13], v[2:5]
	ds_read_b128 v[14:17], v131 offset:53376
	s_lshl_b32 s8, s11, 1
	s_add_u32 s6, s6, s8
	s_waitcnt lgkmcnt(2)
	v_mfma_f32_16x16x32_bf16 v[6:9], v[18:21], v[6:9], 0
	s_addc_u32 s7, s7, 0
	s_add_i32 s2, s2, s50
	s_cmpk_gt_i32 s2, 0xff
	s_waitcnt lgkmcnt(1)
	v_mfma_f32_16x16x32_bf16 v[6:9], v[22:25], v[10:13], v[6:9]
	ds_read_b128 v[10:13], v131 offset:53440
	ds_read_b128 v[18:21], v130 offset:128
	ds_read_b128 v[22:25], v130 offset:192
	s_waitcnt lgkmcnt(1)
	v_mfma_f32_16x16x32_bf16 v[2:5], v[14:17], v[18:21], v[2:5]
	s_waitcnt lgkmcnt(0)
	v_mfma_f32_16x16x32_bf16 v[2:5], v[10:13], v[22:25], v[2:5]
	ds_read_b128 v[10:13], v131 offset:128
	ds_read_b128 v[14:17], v131 offset:192
	s_waitcnt lgkmcnt(1)
	v_mfma_f32_16x16x32_bf16 v[6:9], v[10:13], v[18:21], v[6:9]
	s_nop 3
	v_add_f32_e64 v2, v26, -v2
	v_add_f32_e64 v3, v27, -v3
	v_lshlrev_b32_e32 v27, 16, v146
	v_lshlrev_b32_e32 v26, 16, v105
	v_pk_add_f32 v[4:5], v[26:27], v[4:5] neg_lo:[0,1] neg_hi:[0,1]
	v_cvt_pk_bf16_f32 v2, v2, v3
	v_cvt_pk_bf16_f32 v3, v4, v5
	ds_write_b64 v132, v[2:3]
	s_waitcnt lgkmcnt(0)
	s_barrier
	ds_read_b128 v[2:5], v133
	ds_read_b128 v[10:13], v134
	ds_read_b128 v[18:21], v133 offset:64
	v_mfma_f32_16x16x32_bf16 v[6:9], v[14:17], v[22:25], v[6:9]
	ds_read_b128 v[14:17], v134 offset:64
	v_mov_b32_e32 v105, v1
	s_waitcnt lgkmcnt(2)
	v_mfma_f32_16x16x32_bf16 v[2:5], v[2:5], v[10:13], v[6:9]
	s_nop 3
	v_lshl_add_u64 v[6:7], s[6:7], 0, v[0:1]
	v_lshl_add_u64 v[6:7], v[6:7], 0, v[104:105]
	s_waitcnt lgkmcnt(0)
	v_mfma_f32_16x16x32_bf16 v[2:5], v[18:21], v[14:17], v[2:5]
	s_mov_b64 s[6:7], 0xfc000
	v_lshl_add_u64 v[108:109], v[6:7], 0, s[6:7]
	v_lshl_add_u64 v[6:7], v[66:67], 1, v[108:109]
	s_waitcnt vmcnt(4)
	v_pk_mul_f32 v[20:21], v[106:107], v[32:33] op_sel_hi:[0,1]
	v_pk_mul_f32 v[18:19], v[106:107], v[30:31] op_sel_hi:[0,1]
	s_nop 1
	v_cvt_pk_bf16_f32 v2, v2, s0
	global_store_short v[6:7], v2, off
	ds_read_b128 v[6:9], v135 offset:34816
	v_cvt_pk_bf16_f32 v10, v3, s0
	v_lshl_add_u64 v[2:3], v[70:71], 1, v[108:109]
	global_store_short v[2:3], v10, off
	ds_read_b128 v[10:13], v135 offset:34880
	ds_read_b128 v[14:17], v136
	ds_read_b128 v[22:25], v136 offset:64
	s_waitcnt lgkmcnt(1)
	v_mfma_f32_16x16x32_bf16 v[14:17], v[6:9], v[14:17], v[18:21]
	s_nop 2
	ds_read_b128 v[18:21], v136 offset:2304
	ds_read_b128 v[26:29], v136 offset:2368
	v_cvt_pk_bf16_f32 v4, v4, s0
	s_waitcnt lgkmcnt(2)
	v_mfma_f32_16x16x32_bf16 v[14:17], v[10:13], v[22:25], v[14:17]
	v_mul_f32_e64 v24, v106, v36
	v_mul_f32_e64 v25, v106, v37
	v_pk_mul_f32 v[22:23], v[106:107], v[34:35] op_sel_hi:[0,1]
	v_lshl_add_u64 v[2:3], v[72:73], 1, v[108:109]
	global_store_short v[2:3], v4, off
	s_waitcnt lgkmcnt(1)
	v_mfma_f32_16x16x32_bf16 v[6:9], v[6:9], v[18:21], v[22:25]
	v_cvt_pk_bf16_f32 v4, v5, s0
	v_lshl_add_u64 v[2:3], v[74:75], 1, v[108:109]
	global_store_short v[2:3], v4, off
	s_waitcnt lgkmcnt(0)
	v_mfma_f32_16x16x32_bf16 v[2:5], v[10:13], v[26:29], v[6:9]
	s_nop 2
	v_cvt_pk_bf16_f32 v6, v14, v15
	v_cvt_pk_bf16_f32 v7, v16, v17
	s_nop 2
	v_cvt_pk_bf16_f32 v2, v2, v3
	v_cvt_pk_bf16_f32 v3, v4, v5
	ds_write_b64 v137, v[6:7]
	ds_write_b64 v137, v[2:3] offset:4352
	s_cbranch_scc0 .LBB0_282
